# static priority raise for the S5 chain waves over the co-resident spatial-sample waves
# speedup vs baseline: 1.0027x; 1.0027x over previous
.LBB0_460:
	s_andn2_b64 vcc, exec, s[4:5]
	s_cbranch_vccnz .LBB0_470
	s_or_b32 s4, s69, s64
	s_cmpk_gt_i32 s4, 0x1ff
	s_cbranch_scc1 .LBB0_470
	s_setprio 3
	v_mov_b32_e32 v73, 0
	v_mov_b32_e32 v179, v73
	v_add_u32_e32 v0, s65, v151
	v_add_u32_e32 v1, s65, v224
	s_lshl_b32 s3, s2, 6
	s_lshl_b32 s5, s69, 4
	v_lshl_add_u64 v[74:75], s[38:39], 0, v[178:179]
	v_lshl_add_u64 v[76:77], s[22:23], 0, v[178:179]
	s_add_i32 s17, s3, s5
	s_lshl_b32 s22, s68, 6
	v_or_b32_e32 v104, 32, v142
	v_lshlrev_b32_e32 v72, 1, v148
	v_lshlrev_b32_e32 v105, 1, v150
	s_mov_b32 s7, 0
	v_lshlrev_b32_e32 v78, 1, v147
	v_mov_b32_e32 v79, v73
	v_add_u32_e32 v106, v0, v146
	v_add_u32_e32 v107, s65, v178
	v_add_u32_e32 v108, v1, v149
	s_mov_b32 s10, 0x3dd2d3e7
	s_mov_b32 s16, 0xc0135761
	s_branch .LBB0_464

.LBB0_470:
	s_setprio 0
	s_waitcnt vmcnt(0)
	s_barrier
	s_and_saveexec_b64 s[4:5], s[98:99]
	v_readlane_b32 s30, v254, 8
	s_xor_b64 s[4:5], exec, s[4:5]
	v_readlane_b32 s31, v254, 9
	s_cbranch_execz .LBB0_523
	s_add_i32 s3, 0, 0x21000
	v_mov_b32_e32 v0, s3
	s_waitcnt vmcnt(0) expcnt(0) lgkmcnt(0)
	ds_read_b32 v2, v0
	s_add_i32 s3, 0, 0x21004
	v_mov_b32_e32 v0, s3
	ds_read_b32 v0, v0
	s_waitcnt lgkmcnt(1)
	v_cmp_ne_u32_e32 vcc, 0, v2
	s_cbranch_vccnz .LBB0_486
	s_add_u32 s6, s56, 0x13daa200
	s_addc_u32 s7, s57, 0
	s_add_u32 s10, s56, 0x13daa400
	s_addc_u32 s11, s57, 0
	s_add_u32 s16, s56, 0x13daa500
	s_addc_u32 s17, s57, 0
	s_add_u32 s18, s56, 0x13daa600
	s_addc_u32 s19, s57, 0
	s_add_u32 s20, s56, 0x13daa700
	s_addc_u32 s21, s57, 0
	s_add_u32 s22, s56, 0x13daa800
	s_addc_u32 s23, s57, 0
	s_add_u32 s24, s56, 0x13daa900
	s_addc_u32 s25, s57, 0
	s_add_u32 s26, s56, 0x13daaa00
	s_addc_u32 s27, s57, 0
	s_add_u32 s28, s56, 0x13daab00
	s_addc_u32 s29, s57, 0
	s_add_u32 s34, s56, 0x13daac00
	s_addc_u32 s35, s57, 0
	s_add_u32 s36, s56, 0x13daad00
	s_addc_u32 s37, s57, 0
	s_add_u32 s38, s56, 0x13daae00
	s_addc_u32 s39, s57, 0
	s_add_u32 s40, s56, 0x13daaf00
	s_addc_u32 s41, s57, 0
	s_add_u32 s42, s56, 0x13dab000
	s_addc_u32 s43, s57, 0
	s_add_u32 s44, s56, 0x13dab100
	s_addc_u32 s45, s57, 0
	s_add_u32 s46, s56, 0x13dab200
	s_addc_u32 s47, s57, 0
	s_mul_i32 s3, s31, s92
	s_add_u32 s48, s56, 0x13dab300
	s_mul_i32 s3, s3, s30
	s_addc_u32 s49, s57, 0
	s_mov_b32 s33, 1
	v_mov_b32_e32 v16, 0
	s_branch .LBB0_474
